# strategy 2: attention unit q-prep: q-gain loads of 7 of 8 head-dim slices hoisted above the rsqrt chain and issued together (one wait instead of 14)
# baseline (speedup 1.0000x reference)
.LBB0_508:
	s_abs_i32 s3, s25
	s_mul_hi_u32 s4, s3, s75
	s_mul_i32 s4, s4, s69
	s_sub_i32 s3, s3, s4
	s_ashr_i32 s2, s25, 31
	s_sub_i32 s4, s3, s69
	s_cmp_ge_u32 s3, s69
	s_cselect_b32 s3, s4, s3
	s_sub_i32 s4, s3, s69
	s_cmp_ge_u32 s3, s69
	s_cselect_b32 s3, s4, s3
	s_xor_b32 s3, s3, s2
	s_sub_i32 s4, s3, s2
	s_ashr_i32 s5, s4, 5
	s_lshl_b32 s2, s5, 3
	s_add_i32 s6, s2, s35
	v_readlane_b32 s2, v253, 41
	v_readlane_b32 s3, v253, 42
	s_and_b64 s[2:3], s[2:3], exec
	s_cselect_b32 s3, s6, s5
	s_ashr_i32 s2, s3, 1
	s_and_b32 s6, s3, 1
	s_ashr_i32 s3, s2, 31
	s_lshl_b64 s[8:9], s[2:3], 11
	s_lshl_b32 s3, s4, 8
	s_and_b32 s14, s3, 0x700
	s_or_b32 s8, s8, s14
	s_mul_i32 s3, s9, 0x2400
	s_mul_hi_u32 s5, s8, 0x2400
	s_add_i32 s5, s5, s3
	s_mul_i32 s3, s8, 0x2400
	v_readlane_b32 s10, v253, 31
	v_readlane_b32 s11, v253, 32
	s_add_u32 s3, s10, s3
	s_addc_u32 s5, s11, s5
	s_lshl_b32 s4, s4, 4
	s_lshl_b32 s7, s6, 9
	s_and_b32 s4, s4, 0x180
	s_or_b32 s12, s7, s4
	s_lshl_b32 s4, s12, 1
	s_add_u32 s4, s3, s4
	s_addc_u32 s5, s5, 0
	s_mul_i32 s7, s2, 0x1200000
	s_mul_hi_i32 s3, s2, 0x1200000
	s_add_u32 s7, s10, s7
	s_addc_u32 s10, s11, s3
	s_lshl_b32 s3, s6, 8
	s_add_u32 s6, s7, s3
	s_addc_u32 s7, s10, 0
	v_readlane_b32 s10, v253, 2
	v_readlane_b32 s11, v253, 3
	s_load_dwordx2 s[10:11], s[10:11], 0x28
	v_readlane_b32 s16, v253, 35
	v_readlane_b32 s17, v253, 36
	s_lshl_b64 s[16:17], s[16:17], 2
	s_waitcnt vmcnt(0)
	v_mov_b32_e32 v50, v0
	s_waitcnt lgkmcnt(0)
	s_add_u32 s10, s10, s16
	s_addc_u32 s11, s11, s17
	s_add_i32 s13, 0, 0x1c000
	v_and_b32_e32 v2, 0x3fffffc0, v50
	v_lshl_add_u32 v151, v2, 2, s13
	v_ashrrev_i32_e32 v2, 1, v50
	s_movk_i32 s13, 0xffe0
	v_bfe_u32 v155, v50, 5, 1
	v_and_b32_e32 v150, 0xffffffe0, v2
	v_bfi_b32 v31, s13, v2, v50
	v_mov_b64_e32 v[2:3], s[4:5]
	s_movk_i32 s15, 0x2400
	v_mad_i64_i32 v[2:3], s[4:5], v31, s15, v[2:3]
	v_lshlrev_b32_e32 v202, 4, v155
	v_lshl_add_u64 v[2:3], v[2:3], 0, v[202:203]
	global_load_dwordx4 v[26:29], v[2:3], off
	global_load_dwordx4 v[32:35], v[2:3], off offset:32
	global_load_dwordx4 v[22:25], v[2:3], off offset:64
	global_load_dwordx4 v[14:17], v[2:3], off offset:96
	global_load_dwordx4 v[18:21], v[2:3], off offset:128
	global_load_dwordx4 v[10:13], v[2:3], off offset:160
	global_load_dwordx4 v[6:9], v[2:3], off offset:192
	s_nop 0
	global_load_dwordx4 v[2:5], v[2:3], off offset:224
	s_mov_b32 s4, 0xf800000
	v_and_b32_e32 v154, 31, v50
	v_and_b32_e32 v51, 63, v50
	s_mov_b32 s17, s61
	s_mov_b32 s16, s61
	s_mov_b32 s18, s61
	s_mov_b32 s19, s61
	s_mov_b32 s20, s61
	s_mov_b32 s21, s61
	s_mov_b32 s22, s61
	s_mov_b32 s23, s61
	s_mov_b32 s24, s61
	s_mov_b32 s25, s61
	s_mov_b32 s26, s61
	s_mov_b32 s27, s61
	s_mov_b32 s28, s61
	s_mov_b32 s29, s61
	s_mov_b32 s30, s61
	s_mov_b32 s31, s61
	s_mov_b32 s13, -1
	v_lshl_add_u32 v157, v154, 2, v151
	v_mov_b32_e32 v165, 0
	s_waitcnt vmcnt(7)
	v_and_b32_e32 v72, 0xffff0000, v26
	v_and_b32_e32 v74, 0xffff0000, v27
	v_lshlrev_b32_e32 v71, 16, v26
	v_mul_f32_e32 v26, v72, v72
	v_lshlrev_b32_e32 v73, 16, v27
	v_mul_f32_e32 v27, v74, v74
	v_fmac_f32_e32 v26, v71, v71
	v_fmac_f32_e32 v27, v73, v73
	v_and_b32_e32 v79, 0xffff0000, v28
	v_add_f32_e32 v26, v26, v27
	v_lshlrev_b32_e32 v78, 16, v28
	v_mul_f32_e32 v27, v79, v79
	v_fmac_f32_e32 v27, v78, v78
	v_and_b32_e32 v81, 0xffff0000, v29
	s_waitcnt vmcnt(4)
	v_and_b32_e32 v61, 0xffff0000, v14
	v_and_b32_e32 v58, 0xffff0000, v15
	v_add_f32_e32 v26, v27, v26
	v_lshlrev_b32_e32 v80, 16, v29
	v_mul_f32_e32 v27, v81, v81
	v_lshlrev_b32_e32 v60, 16, v14
	v_mul_f32_e32 v14, v61, v61
	v_lshlrev_b32_e32 v59, 16, v15
	v_mul_f32_e32 v15, v58, v58
	v_fmac_f32_e32 v27, v80, v80
	v_and_b32_e32 v64, 0xffff0000, v32
	v_and_b32_e32 v66, 0xffff0000, v33
	v_fmac_f32_e32 v14, v60, v60
	v_fmac_f32_e32 v15, v59, v59
	v_and_b32_e32 v57, 0xffff0000, v16
	v_add_f32_e32 v26, v27, v26
	v_lshlrev_b32_e32 v63, 16, v32
	v_mul_f32_e32 v27, v64, v64
	v_lshlrev_b32_e32 v65, 16, v33
	v_mul_f32_e32 v28, v66, v66
	v_and_b32_e32 v49, 0xffff0000, v22
	v_and_b32_e32 v55, 0xffff0000, v23
	v_add_f32_e32 v14, v14, v15
	v_lshlrev_b32_e32 v56, 16, v16
	v_mul_f32_e32 v15, v57, v57
	v_fmac_f32_e32 v27, v63, v63
	v_fmac_f32_e32 v28, v65, v65
	v_and_b32_e32 v68, 0xffff0000, v34
	v_lshlrev_b32_e32 v48, 16, v22
	v_mul_f32_e32 v22, v49, v49
	v_lshlrev_b32_e32 v54, 16, v23
	v_mul_f32_e32 v23, v55, v55
	v_fmac_f32_e32 v15, v56, v56
	v_and_b32_e32 v53, 0xffff0000, v17
	v_add_f32_e32 v27, v27, v28
	v_lshlrev_b32_e32 v67, 16, v34
	v_mul_f32_e32 v28, v68, v68
	v_fmac_f32_e32 v22, v48, v48
	v_fmac_f32_e32 v23, v54, v54
	v_and_b32_e32 v77, 0xffff0000, v24
	v_add_f32_e32 v14, v15, v14
	v_lshlrev_b32_e32 v52, 16, v17
	v_mul_f32_e32 v15, v53, v53
	v_fmac_f32_e32 v28, v67, v67
	v_and_b32_e32 v70, 0xffff0000, v35
	v_add_f32_e32 v22, v22, v23
	v_lshlrev_b32_e32 v62, 16, v24
	v_mul_f32_e32 v23, v77, v77
	v_fmac_f32_e32 v15, v52, v52
	s_waitcnt vmcnt(3)
	v_and_b32_e32 v47, 0xffff0000, v18
	v_and_b32_e32 v45, 0xffff0000, v19
	v_add_f32_e32 v27, v28, v27
	v_lshlrev_b32_e32 v69, 16, v35
	v_mul_f32_e32 v28, v70, v70
	v_fmac_f32_e32 v23, v62, v62
	v_and_b32_e32 v76, 0xffff0000, v25
	v_add_f32_e32 v14, v15, v14
	v_lshlrev_b32_e32 v46, 16, v18
	v_mul_f32_e32 v15, v47, v47
	v_lshlrev_b32_e32 v44, 16, v19
	v_mul_f32_e32 v16, v45, v45
	s_waitcnt vmcnt(2)
	v_and_b32_e32 v39, 0xffff0000, v10
	v_and_b32_e32 v37, 0xffff0000, v11
	v_fmac_f32_e32 v28, v69, v69
	v_add_f32_e32 v22, v23, v22
	v_lshlrev_b32_e32 v75, 16, v25
	v_mul_f32_e32 v23, v76, v76
	v_fmac_f32_e32 v15, v46, v46
	v_fmac_f32_e32 v16, v44, v44
	v_and_b32_e32 v43, 0xffff0000, v20
	v_lshlrev_b32_e32 v38, 16, v10
	v_mul_f32_e32 v10, v39, v39
	v_lshlrev_b32_e32 v36, 16, v11
	v_mul_f32_e32 v11, v37, v37
	v_add_f32_e32 v27, v28, v27
	v_fmac_f32_e32 v23, v75, v75
	v_add_f32_e32 v15, v15, v16
	v_lshlrev_b32_e32 v42, 16, v20
	v_mul_f32_e32 v16, v43, v43
	v_fmac_f32_e32 v10, v38, v38
	v_fmac_f32_e32 v11, v36, v36
	v_and_b32_e32 v35, 0xffff0000, v12
	s_waitcnt vmcnt(1)
	v_and_b32_e32 v30, 0xffff0000, v6
	v_and_b32_e32 v28, 0xffff0000, v7
	v_add_f32_e32 v26, v26, v27
	v_add_f32_e32 v22, v23, v22
	v_fmac_f32_e32 v16, v42, v42
	v_lshlrev_b32_e32 v40, 16, v21
	v_and_b32_e32 v41, 0xffff0000, v21
	v_add_f32_e32 v10, v10, v11
	v_lshlrev_b32_e32 v34, 16, v12
	v_mul_f32_e32 v11, v35, v35
	v_lshlrev_b32_e32 v29, 16, v6
	v_mul_f32_e32 v6, v30, v30
	v_lshlrev_b32_e32 v27, 16, v7
	v_mul_f32_e32 v7, v28, v28
	s_waitcnt vmcnt(0)
	v_and_b32_e32 v216, 32, v50
	global_load_dwordx4 v[90:93], v216, s[10:11] offset:16
	global_load_dwordx4 v[94:97], v216, s[10:11]
	global_load_dwordx4 v[130:133], v216, s[10:11] offset:80
	global_load_dwordx4 v[134:137], v216, s[10:11] offset:64
	global_load_dwordx4 v[138:141], v216, s[10:11] offset:144
	global_load_dwordx4 v[142:145], v216, s[10:11] offset:128
	global_load_dwordx4 v[146:149], v216, s[10:11] offset:208
	global_load_dwordx4 v[186:189], v216, s[10:11] offset:192
	global_load_dwordx4 v[190:193], v216, s[10:11] offset:272
	global_load_dwordx4 v[194:197], v216, s[10:11] offset:256
	global_load_dwordx4 v[204:207], v216, s[10:11] offset:336
	global_load_dwordx4 v[212:215], v216, s[10:11] offset:320
	global_load_dwordx4 v[218:221], v216, s[10:11] offset:400
	global_load_dwordx4 v[222:225], v216, s[10:11] offset:384
	v_and_b32_e32 v21, 0xffff0000, v2
	v_and_b32_e32 v19, 0xffff0000, v3
	v_add_f32_e32 v22, v26, v22
	v_add_f32_e32 v15, v16, v15
	v_mul_f32_e32 v16, v41, v41
	v_fmac_f32_e32 v11, v34, v34
	v_and_b32_e32 v33, 0xffff0000, v13
	v_fmac_f32_e32 v6, v29, v29
	v_fmac_f32_e32 v7, v27, v27
	v_and_b32_e32 v26, 0xffff0000, v8
	v_lshlrev_b32_e32 v20, 16, v2
	v_mul_f32_e32 v2, v21, v21
	v_lshlrev_b32_e32 v18, 16, v3
	v_mul_f32_e32 v3, v19, v19
	v_fmac_f32_e32 v16, v40, v40
	v_add_f32_e32 v10, v11, v10
	v_lshlrev_b32_e32 v32, 16, v13
	v_mul_f32_e32 v11, v33, v33
	v_add_f32_e32 v6, v6, v7
	v_lshlrev_b32_e32 v25, 16, v8
	v_mul_f32_e32 v7, v26, v26
	v_fmac_f32_e32 v2, v20, v20
	v_fmac_f32_e32 v3, v18, v18
	v_and_b32_e32 v17, 0xffff0000, v4
	v_add_f32_e32 v14, v22, v14
	v_add_f32_e32 v15, v16, v15
	v_fmac_f32_e32 v11, v32, v32
	v_fmac_f32_e32 v7, v25, v25
	v_and_b32_e32 v24, 0xffff0000, v9
	v_add_f32_e32 v2, v2, v3
	v_lshlrev_b32_e32 v16, 16, v4
	v_mul_f32_e32 v3, v17, v17
	v_add_f32_e32 v14, v14, v15
	v_add_f32_e32 v10, v11, v10
	v_add_f32_e32 v6, v7, v6
	v_lshlrev_b32_e32 v23, 16, v9
	v_mul_f32_e32 v7, v24, v24
	v_fmac_f32_e32 v3, v16, v16
	v_and_b32_e32 v15, 0xffff0000, v5
	v_add_f32_e32 v10, v14, v10
	v_fmac_f32_e32 v7, v23, v23
	v_add_f32_e32 v2, v3, v2
	v_lshlrev_b32_e32 v14, 16, v5
	v_mul_f32_e32 v3, v15, v15
	v_add_f32_e32 v6, v7, v6
	v_fmac_f32_e32 v3, v14, v14
	v_add_f32_e32 v6, v10, v6
	v_add_f32_e32 v2, v3, v2
	v_add_f32_e32 v2, v6, v2
	v_mov_b32_e32 v3, v2
	s_nop 1
	v_permlane32_swap_b32_e32 v2, v3
	v_add_f32_e32 v2, v2, v3
	v_fmamk_f32 v2, v2, 0x3c000000, v217
	v_cmp_gt_f32_e32 vcc, s4, v2
	v_mul_f32_e32 v3, 0x4f800000, v2
	v_and_b32_e32 v10, 32, v50
	v_cndmask_b32_e32 v2, v2, v3, vcc
	v_sqrt_f32_e32 v3, v2
	v_or_b32_e32 v11, s14, v154
	v_add_u32_e32 v4, -1, v3
	v_fma_f32 v5, -v4, v3, v2
	v_cmp_ge_f32_e64 s[4:5], 0, v5
	v_add_u32_e32 v5, 1, v3
	s_nop 0
	v_cndmask_b32_e64 v4, v3, v4, s[4:5]
	v_fma_f32 v3, -v5, v3, v2
	v_cmp_lt_f32_e64 s[4:5], 0, v3
	s_nop 1
	v_cndmask_b32_e64 v3, v4, v5, s[4:5]
	v_mul_f32_e32 v4, 0x37800000, v3
	v_cndmask_b32_e32 v3, v3, v4, vcc
	v_cmp_class_f32_e32 vcc, v2, v228
	s_nop 1
	v_cndmask_b32_e32 v2, v3, v2, vcc
	v_div_scale_f32 v3, s[4:5], v2, v2, 1.0
	v_rcp_f32_e32 v4, v3
	v_readlane_b32 s4, v253, 39
	v_readlane_b32 s5, v253, 40
	v_fma_f32 v5, -v3, v4, 1.0
	v_fmac_f32_e32 v4, v5, v4
	v_div_scale_f32 v5, vcc, 1.0, v2, 1.0
	v_mul_f32_e32 v6, v5, v4
	v_fma_f32 v7, -v3, v6, v5
	v_fmac_f32_e32 v6, v7, v4
	v_fma_f32 v3, -v3, v6, v5
	v_div_fmas_f32 v3, v3, v4, v6
	v_div_fixup_f32 v22, v3, v2, 1.0
	s_waitcnt vmcnt(0)
	v_mov_b32_e32 v2, v90
	v_mov_b32_e32 v3, v91
	v_mov_b32_e32 v4, v92
	v_mov_b32_e32 v5, v93
	v_mov_b32_e32 v6, v94
	v_mov_b32_e32 v7, v95
	v_mov_b32_e32 v8, v96
	v_mov_b32_e32 v9, v97
	s_waitcnt vmcnt(1)
	v_mul_f32_e32 v89, v2, v22
	v_add_u32_e32 v2, v11, v150
	v_ashrrev_i32_e32 v2, 1, v2
	v_and_b32_e32 v2, 0xffffffe0, v2
	v_mul_f32_e32 v88, v3, v22
	v_ashrrev_i32_e32 v3, 31, v2
	v_lshl_add_u64 v[2:3], v[2:3], 3, s[4:5]
	v_mov_b32_e32 v11, v203
	v_lshl_add_u64 v[12:13], v[2:3], 0, v[10:11]
	s_waitcnt vmcnt(0)
	v_mul_f32_e32 v82, v9, v22
	v_mul_f32_e32 v83, v8, v22
	v_mul_f32_e32 v84, v7, v22
	v_mul_f32_e32 v85, v6, v22
	v_mul_f32_e32 v86, v5, v22
	v_mul_f32_e32 v87, v4, v22
	global_load_dwordx4 v[2:5], v[12:13], off offset:16
	global_load_dwordx4 v[6:9], v[12:13], off
	v_mul_f32_e32 v72, v84, v72
	v_mul_f32_e32 v71, v85, v71
	s_waitcnt vmcnt(0)
	v_mul_f32_e32 v84, v7, v72
	v_fma_f32 v84, v6, v71, -v84
	v_mul_f32_e32 v6, v6, v72
	v_fmac_f32_e32 v6, v7, v71
	v_mul_f32_e32 v7, v82, v74
	v_cvt_pk_bf16_f32 v98, v84, v6
	v_mul_f32_e32 v6, v83, v73
	v_mul_f32_e32 v71, v9, v7
	v_mul_f32_e32 v7, v8, v7
	v_fmac_f32_e32 v7, v9, v6
	v_fma_f32 v71, v8, v6, -v71
	v_cvt_pk_bf16_f32 v99, v71, v7
	v_mul_f32_e32 v7, v88, v79
	v_mul_f32_e32 v6, v89, v78
	v_mul_f32_e32 v8, v3, v7
	v_fma_f32 v8, v2, v6, -v8
	v_mul_f32_e32 v2, v2, v7
	v_fmac_f32_e32 v2, v3, v6
	v_mul_f32_e32 v3, v86, v81
	v_cvt_pk_bf16_f32 v100, v8, v2
	v_mul_f32_e32 v2, v87, v80
	v_mul_f32_e32 v6, v5, v3
	v_mul_f32_e32 v3, v4, v3
	v_fma_f32 v6, v4, v2, -v6
	v_fmac_f32_e32 v3, v5, v2
	v_cvt_pk_bf16_f32 v101, v6, v3
	v_mov_b32_e32 v2, v130
	v_mov_b32_e32 v3, v131
	v_mov_b32_e32 v4, v132
	v_mov_b32_e32 v5, v133
	v_mov_b32_e32 v6, v134
	v_mov_b32_e32 v7, v135
	v_mov_b32_e32 v8, v136
	v_mov_b32_e32 v9, v137
	s_waitcnt vmcnt(1)
	v_mul_f32_e32 v78, v22, v5
	s_waitcnt vmcnt(0)
	v_mul_f32_e32 v71, v22, v9
	v_mul_f32_e32 v72, v22, v8
	v_mul_f32_e32 v73, v22, v7
	v_mul_f32_e32 v74, v22, v6
	v_mul_f32_e32 v79, v22, v4
	v_mul_f32_e32 v80, v22, v3
	v_mul_f32_e32 v81, v22, v2
	global_load_dwordx4 v[2:5], v[12:13], off offset:80
	global_load_dwordx4 v[6:9], v[12:13], off offset:64
	v_mul_f32_e32 v64, v73, v64
	v_mul_f32_e32 v63, v74, v63
	s_waitcnt vmcnt(0)
	v_mul_f32_e32 v73, v64, v7
	v_fma_f32 v73, v63, v6, -v73
	v_mul_f32_e32 v6, v64, v6
	v_fmac_f32_e32 v6, v63, v7
	v_mul_f32_e32 v7, v71, v66
	v_cvt_pk_bf16_f32 v102, v73, v6
	v_mul_f32_e32 v6, v72, v65
	v_mul_f32_e32 v63, v7, v9
	v_mul_f32_e32 v7, v7, v8
	v_fmac_f32_e32 v7, v6, v9
	v_fma_f32 v63, v6, v8, -v63
	v_cvt_pk_bf16_f32 v103, v63, v7
	v_mul_f32_e32 v7, v80, v68
	v_mul_f32_e32 v6, v81, v67
	v_mul_f32_e32 v8, v7, v3
	v_fma_f32 v8, v6, v2, -v8
	v_mul_f32_e32 v2, v7, v2
	v_fmac_f32_e32 v2, v6, v3
	v_mul_f32_e32 v3, v78, v70
	v_cvt_pk_bf16_f32 v104, v8, v2
	v_mul_f32_e32 v2, v79, v69
	v_mul_f32_e32 v6, v3, v5
	v_mul_f32_e32 v3, v3, v4
	v_fma_f32 v6, v2, v4, -v6
	v_fmac_f32_e32 v3, v2, v5
	v_cvt_pk_bf16_f32 v105, v6, v3
	v_mov_b32_e32 v2, v138
	v_mov_b32_e32 v3, v139
	v_mov_b32_e32 v4, v140
	v_mov_b32_e32 v5, v141
	v_mov_b32_e32 v6, v142
	v_mov_b32_e32 v7, v143
	v_mov_b32_e32 v8, v144
	v_mov_b32_e32 v9, v145
	s_waitcnt vmcnt(1)
	v_mul_f32_e32 v67, v22, v5
	s_waitcnt vmcnt(0)
	v_mul_f32_e32 v63, v22, v9
	v_mul_f32_e32 v64, v22, v8
	v_mul_f32_e32 v65, v22, v7
	v_mul_f32_e32 v66, v22, v6
	v_mul_f32_e32 v68, v22, v4
	v_mul_f32_e32 v69, v22, v3
	v_mul_f32_e32 v70, v22, v2
	global_load_dwordx4 v[2:5], v[12:13], off offset:144
	global_load_dwordx4 v[6:9], v[12:13], off offset:128
	v_mul_f32_e32 v49, v65, v49
	v_mul_f32_e32 v48, v66, v48
	s_waitcnt vmcnt(0)
	v_mul_f32_e32 v65, v49, v7
	v_fma_f32 v65, v48, v6, -v65
	v_mul_f32_e32 v6, v49, v6
	v_fmac_f32_e32 v6, v48, v7
	v_mul_f32_e32 v7, v63, v55
	v_cvt_pk_bf16_f32 v106, v65, v6
	v_mul_f32_e32 v6, v64, v54
	v_mul_f32_e32 v48, v7, v9
	v_mul_f32_e32 v7, v7, v8
	v_fmac_f32_e32 v7, v6, v9
	v_fma_f32 v48, v6, v8, -v48
	v_cvt_pk_bf16_f32 v107, v48, v7
	v_mul_f32_e32 v7, v69, v77
	v_mul_f32_e32 v6, v70, v62
	v_mul_f32_e32 v8, v7, v3
	v_fma_f32 v8, v6, v2, -v8
	v_mul_f32_e32 v2, v7, v2
	v_fmac_f32_e32 v2, v6, v3
	v_mul_f32_e32 v3, v67, v76
	v_cvt_pk_bf16_f32 v108, v8, v2
	v_mul_f32_e32 v2, v68, v75
	v_mul_f32_e32 v6, v3, v5
	v_mul_f32_e32 v3, v3, v4
	v_fma_f32 v6, v2, v4, -v6
	v_fmac_f32_e32 v3, v2, v5
	v_cvt_pk_bf16_f32 v109, v6, v3
	v_mov_b32_e32 v2, v146
	v_mov_b32_e32 v3, v147
	v_mov_b32_e32 v4, v148
	v_mov_b32_e32 v5, v149
	v_mov_b32_e32 v6, v186
	v_mov_b32_e32 v7, v187
	v_mov_b32_e32 v8, v188
	v_mov_b32_e32 v9, v189
	s_waitcnt vmcnt(1)
	v_mul_f32_e32 v62, v22, v5
	s_waitcnt vmcnt(0)
	v_mul_f32_e32 v48, v22, v9
	v_mul_f32_e32 v49, v22, v8
	v_mul_f32_e32 v54, v22, v7
	v_mul_f32_e32 v55, v22, v6
	v_mul_f32_e32 v63, v22, v4
	v_mul_f32_e32 v64, v22, v3
	v_mul_f32_e32 v65, v22, v2
	global_load_dwordx4 v[2:5], v[12:13], off offset:208
	global_load_dwordx4 v[6:9], v[12:13], off offset:192
	v_mul_f32_e32 v13, v54, v61
	v_mul_f32_e32 v12, v55, v60
	v_or_b32_e32 v60, 32, v202
	s_waitcnt vmcnt(0)
	v_mul_f32_e32 v54, v13, v7
	v_fma_f32 v54, v12, v6, -v54
	v_mul_f32_e32 v6, v13, v6
	v_fmac_f32_e32 v6, v12, v7
	v_mul_f32_e32 v7, v48, v58
	v_cvt_pk_bf16_f32 v110, v54, v6
	v_mul_f32_e32 v6, v49, v59
	v_mul_f32_e32 v12, v7, v9
	v_mul_f32_e32 v7, v7, v8
	v_fmac_f32_e32 v7, v6, v9
	v_fma_f32 v12, v6, v8, -v12
	v_cvt_pk_bf16_f32 v111, v12, v7
	v_mul_f32_e32 v7, v64, v57
	v_mul_f32_e32 v6, v65, v56
	v_mul_f32_e32 v8, v7, v3
	v_fma_f32 v8, v6, v2, -v8
	v_mul_f32_e32 v2, v7, v2
	v_fmac_f32_e32 v2, v6, v3
	v_mul_f32_e32 v3, v62, v53
	v_cvt_pk_bf16_f32 v112, v8, v2
	v_mul_f32_e32 v2, v63, v52
	v_mul_f32_e32 v6, v3, v5
	v_mul_f32_e32 v3, v3, v4
	v_fma_f32 v6, v2, v4, -v6
	v_fmac_f32_e32 v3, v2, v5
	v_cvt_pk_bf16_f32 v113, v6, v3
	v_mov_b32_e32 v2, v190
	v_mov_b32_e32 v3, v191
	v_mov_b32_e32 v4, v192
	v_mov_b32_e32 v5, v193
	v_mov_b32_e32 v6, v194
	v_mov_b32_e32 v7, v195
	v_mov_b32_e32 v8, v196
	v_mov_b32_e32 v9, v197
	v_lshlrev_b32_e32 v59, 8, v154
	s_waitcnt vmcnt(1)
	v_mul_f32_e32 v57, v22, v2
	v_lshlrev_b32_e32 v2, 8, v31
	v_mul_f32_e32 v56, v22, v3
	v_and_b32_e32 v2, 0x3f00, v2
	v_mov_b32_e32 v3, v203
	v_lshl_add_u64 v[2:3], s[4:5], 0, v[2:3]
	v_lshl_add_u64 v[2:3], v[2:3], 0, v[10:11]
	s_waitcnt vmcnt(0)
	v_mul_f32_e32 v12, v22, v7
	v_mul_f32_e32 v13, v22, v6
	v_mul_f32_e32 v48, v22, v5
	v_mul_f32_e32 v49, v22, v4
	global_load_dwordx4 v[4:7], v[2:3], off offset:16
	global_load_dwordx4 v[52:55], v[2:3], off
	v_mul_f32_e32 v9, v22, v9
	v_mul_f32_e32 v12, v12, v47
	v_mul_f32_e32 v8, v22, v8
	v_mul_f32_e32 v11, v13, v46
	v_mul_f32_e32 v9, v9, v45
	v_mul_f32_e32 v8, v8, v44
	s_add_i32 s4, 0, 0xc000
	s_cmp_lg_u32 s4, -1
	s_waitcnt vmcnt(0)
	v_mul_f32_e32 v13, v12, v53
	v_mul_f32_e32 v12, v12, v52
	v_fma_f32 v13, v11, v52, -v13
	v_fmac_f32_e32 v12, v11, v53
	v_mul_f32_e32 v11, v9, v55
	v_mul_f32_e32 v9, v9, v54
	v_fmac_f32_e32 v9, v8, v55
	v_cvt_pk_bf16_f32 v114, v13, v12
	v_fma_f32 v11, v8, v54, -v11
	v_cvt_pk_bf16_f32 v115, v11, v9
	v_mul_f32_e32 v9, v56, v43
	v_mul_f32_e32 v8, v57, v42
	v_mul_f32_e32 v11, v9, v5
	v_fma_f32 v11, v8, v4, -v11
	v_mul_f32_e32 v4, v9, v4
	v_fmac_f32_e32 v4, v8, v5
	v_mul_f32_e32 v5, v48, v41
	v_cvt_pk_bf16_f32 v116, v11, v4
	v_mul_f32_e32 v4, v49, v40
	v_mul_f32_e32 v8, v5, v7
	v_mul_f32_e32 v5, v5, v6
	v_fmac_f32_e32 v5, v4, v7
	v_fma_f32 v8, v4, v6, -v8
	v_cvt_pk_bf16_f32 v117, v8, v5
	v_mov_b32_e32 v4, v204
	v_mov_b32_e32 v5, v205
	v_mov_b32_e32 v6, v206
	v_mov_b32_e32 v7, v207
	v_mov_b32_e32 v40, v212
	v_mov_b32_e32 v41, v213
	v_mov_b32_e32 v42, v214
	v_mov_b32_e32 v43, v215
	v_ashrrev_i32_e32 v52, 4, v50
	s_waitcnt vmcnt(1)
	v_mul_f32_e32 v13, v22, v7
	s_waitcnt vmcnt(0)
	v_mul_f32_e32 v8, v22, v43
	v_mul_f32_e32 v9, v22, v42
	v_mul_f32_e32 v11, v22, v41
	v_mul_f32_e32 v12, v22, v40
	v_mul_f32_e32 v31, v22, v6
	v_mul_f32_e32 v44, v22, v5
	v_mul_f32_e32 v45, v22, v4
	global_load_dwordx4 v[4:7], v[2:3], off offset:80
	global_load_dwordx4 v[40:43], v[2:3], off offset:64
	v_mul_f32_e32 v11, v11, v39
	v_mul_f32_e32 v12, v12, v38
	v_mul_f32_e32 v8, v8, v37
	v_mul_f32_e32 v9, v9, v36
	s_waitcnt vmcnt(0)
	v_mul_f32_e32 v38, v11, v41
	v_mul_f32_e32 v11, v11, v40
	v_fmac_f32_e32 v11, v12, v41
	v_fma_f32 v38, v12, v40, -v38
	v_cvt_pk_bf16_f32 v118, v38, v11
	v_mul_f32_e32 v11, v8, v43
	v_mul_f32_e32 v8, v8, v42
	v_fma_f32 v11, v9, v42, -v11
	v_fmac_f32_e32 v8, v9, v43
	v_mul_f32_e32 v9, v44, v35
	v_cvt_pk_bf16_f32 v119, v11, v8
	v_mul_f32_e32 v8, v45, v34
	v_mul_f32_e32 v11, v9, v5
	v_fma_f32 v11, v8, v4, -v11
	v_mul_f32_e32 v4, v9, v4
	v_fmac_f32_e32 v4, v8, v5
	v_mul_f32_e32 v5, v13, v33
	v_cvt_pk_bf16_f32 v120, v11, v4
	v_mul_f32_e32 v4, v31, v32
	v_mul_f32_e32 v8, v5, v7
	v_mul_f32_e32 v5, v5, v6
	v_fmac_f32_e32 v5, v4, v7
	v_fma_f32 v8, v4, v6, -v8
	v_cvt_pk_bf16_f32 v121, v8, v5
	v_mov_b32_e32 v4, v218
	v_mov_b32_e32 v5, v219
	v_mov_b32_e32 v6, v220
	v_mov_b32_e32 v7, v221
	v_mov_b32_e32 v32, v222
	v_mov_b32_e32 v33, v223
	v_mov_b32_e32 v34, v224
	v_mov_b32_e32 v35, v225
	s_waitcnt vmcnt(1)
	v_mul_f32_e32 v13, v22, v7
	s_waitcnt vmcnt(0)
	v_mul_f32_e32 v8, v22, v35
	v_mul_f32_e32 v9, v22, v34
	v_mul_f32_e32 v11, v22, v33
	v_mul_f32_e32 v12, v22, v32
	v_mul_f32_e32 v31, v22, v6
	v_mul_f32_e32 v36, v22, v5
	v_mul_f32_e32 v37, v22, v4
	global_load_dwordx4 v[4:7], v[2:3], off offset:144
	global_load_dwordx4 v[32:35], v[2:3], off offset:128
	v_mul_f32_e32 v11, v11, v30
	v_mul_f32_e32 v12, v12, v29
	v_mul_f32_e32 v8, v8, v28
	v_mul_f32_e32 v9, v9, v27
	s_waitcnt vmcnt(0)
	v_mul_f32_e32 v29, v11, v33
	v_mul_f32_e32 v11, v11, v32
	v_fmac_f32_e32 v11, v12, v33
	v_fma_f32 v29, v12, v32, -v29
	v_cvt_pk_bf16_f32 v122, v29, v11
	v_mul_f32_e32 v11, v8, v35
	v_mul_f32_e32 v8, v8, v34
	v_fma_f32 v11, v9, v34, -v11
	v_fmac_f32_e32 v8, v9, v35
	v_mul_f32_e32 v9, v36, v26
	v_cvt_pk_bf16_f32 v123, v11, v8
	v_mul_f32_e32 v8, v37, v25
	v_mul_f32_e32 v11, v9, v5
	v_fma_f32 v11, v8, v4, -v11
	v_mul_f32_e32 v4, v9, v4
	v_fmac_f32_e32 v4, v8, v5
	v_mul_f32_e32 v5, v13, v24
	v_cvt_pk_bf16_f32 v124, v11, v4
	v_mul_f32_e32 v4, v31, v23
	v_mul_f32_e32 v8, v5, v7
	v_mul_f32_e32 v5, v5, v6
	v_fma_f32 v8, v4, v6, -v8
	v_fmac_f32_e32 v5, v4, v7
	v_cvt_pk_bf16_f32 v125, v8, v5
	global_load_dwordx4 v[4:7], v10, s[10:11] offset:464
	s_nop 0
	global_load_dwordx4 v[8:11], v10, s[10:11] offset:448
	s_movk_i32 s10, 0x1200
	s_cselect_b32 s11, s4, 0
	s_waitcnt vmcnt(1)
	v_mul_f32_e32 v25, v22, v7
	s_waitcnt vmcnt(0)
	v_mul_f32_e32 v12, v22, v11
	v_mul_f32_e32 v13, v22, v10
	v_mul_f32_e32 v23, v22, v9
	v_mul_f32_e32 v24, v22, v8
	v_mul_f32_e32 v26, v22, v6
	v_mul_f32_e32 v27, v22, v5
	v_mul_f32_e32 v22, v22, v4
	global_load_dwordx4 v[4:7], v[2:3], off offset:208
	global_load_dwordx4 v[8:11], v[2:3], off offset:192
	v_mul_f32_e32 v3, v23, v21
	v_mul_f32_e32 v2, v24, v20
	s_waitcnt vmcnt(0)
	v_mul_f32_e32 v20, v3, v9
	v_mul_f32_e32 v3, v3, v8
	v_fmac_f32_e32 v3, v2, v9
	v_fma_f32 v20, v2, v8, -v20
	v_cvt_pk_bf16_f32 v126, v20, v3
	v_mul_f32_e32 v3, v12, v19
	v_mul_f32_e32 v2, v13, v18
	v_mul_f32_e32 v8, v3, v11
	v_mul_f32_e32 v3, v3, v10
	v_fmac_f32_e32 v3, v2, v11
	v_fma_f32 v8, v2, v10, -v8
	v_cvt_pk_bf16_f32 v127, v8, v3
	v_mul_f32_e32 v3, v27, v17
	v_mul_f32_e32 v2, v22, v16
	v_mul_f32_e32 v8, v3, v5
	v_mul_f32_e32 v3, v3, v4
	v_fmac_f32_e32 v3, v2, v5
	v_fma_f32 v8, v2, v4, -v8
	v_cvt_pk_bf16_f32 v128, v8, v3
	v_mul_f32_e32 v3, v25, v15
	v_mul_f32_e32 v2, v26, v14
	v_mul_f32_e32 v4, v3, v7
	v_mul_f32_e32 v3, v3, v6
	v_fma_f32 v4, v2, v6, -v4
	v_fmac_f32_e32 v3, v2, v7
	v_cvt_pk_bf16_f32 v129, v4, v3
	v_and_b32_e32 v3, 0xfffff0, v52
	v_lshlrev_b32_e32 v4, 1, v52
	v_lshlrev_b32_e32 v2, 3, v50
	v_and_or_b32 v3, v4, 8, v3
	v_and_b32_e32 v53, 0x78, v2
	v_lshrrev_b32_e32 v4, 1, v52
	v_lshrrev_b32_e32 v3, 1, v3
	v_bfe_u32 v2, v2, 5, 2
	v_and_b32_e32 v5, 3, v52
	v_or_b32_e32 v3, v3, v2
	v_and_or_b32 v4, v4, 4, v5
	v_lshlrev_b32_e32 v18, 1, v53
	v_lshlrev_b32_e32 v3, 9, v3
	v_lshlrev_b32_e32 v4, 6, v4
	v_and_b32_e32 v5, 48, v18
	v_add_u32_e32 v19, 32, v52
	v_or3_b32 v54, v3, v4, v5
	v_and_b32_e32 v3, 0xfffff0, v19
	v_lshlrev_b32_e32 v6, 1, v19
	v_and_or_b32 v3, v6, 8, v3
	v_lshrrev_b32_e32 v3, 1, v3
	v_or_b32_e32 v2, v3, v2
	v_lshlrev_b32_e32 v2, 9, v2
	v_lshlrev_b32_e32 v20, 4, v50
	v_or3_b32 v56, v2, v4, v5
	v_lshlrev_b32_e32 v2, 3, v51
	v_and_b32_e32 v3, 0xc0, v20
	v_lshlrev_b32_e32 v4, 1, v50
	v_and_or_b32 v3, v2, 24, v3
	v_and_b32_e32 v4, 32, v4
	v_and_b32_e32 v2, 0x100, v2
	v_or3_b32 v55, v3, v4, v2
	v_mad_i64_i32 v[2:3], s[4:5], v52, s10, 0
	v_or_b32_e32 v2, v2, v53
	v_lshl_add_u64 v[10:11], v[2:3], 1, s[6:7]
	global_load_dwordx4 v[2:5], v[10:11], off offset:2560
	v_mad_i64_i32 v[6:7], s[4:5], v19, s10, 0
	v_or_b32_e32 v6, v6, v53
	v_lshl_add_u64 v[14:15], v[6:7], 1, s[6:7]
	global_load_dwordx4 v[6:9], v[14:15], off offset:2560
	s_nop 0
	global_load_dwordx4 v[10:13], v[10:11], off offset:2048
	s_nop 0
	global_load_dwordx4 v[14:17], v[14:15], off offset:2048
	v_add_u32_e32 v159, 0, v54
	s_waitcnt vmcnt(0)
	v_and_b32_e32 v68, 0x70, v20
	s_add_i32 s4, 0, 0x14000
	v_bitop3_b32 v163, v202, v59, v68 bitop3:0xde
	v_add_u32_e32 v160, 0, v56
	v_add_u32_e32 v164, s4, v163
	v_bitop3_b32 v166, v60, v59, v68 bitop3:0xde
	v_add_u32_e32 v167, s4, v166
	v_add_u32_e32 v156, s11, v55
	s_waitcnt vmcnt(3)
	ds_write_b128 v159, v[2:5] offset:49152
	v_lshlrev_b32_e32 v2, 8, v52
	v_and_b32_e32 v3, 0x70, v50
	v_bitop3_b32 v57, v18, v2, v3 bitop3:0xde
	v_lshlrev_b32_e32 v2, 8, v19
	v_bitop3_b32 v58, v18, v2, v3 bitop3:0xde
	v_add_u32_e32 v161, s4, v57
	v_add_u32_e32 v162, s4, v58
	s_waitcnt vmcnt(2)
	ds_write_b128 v160, v[6:9] offset:49152
	s_waitcnt vmcnt(1)
	ds_write_b128 v161, v[10:13]
	s_waitcnt vmcnt(0)
	ds_write_b128 v162, v[14:17]
	s_waitcnt lgkmcnt(0)
	s_barrier
	ds_read_b128 v[18:21], v164
	ds_read_b128 v[22:25], v164 offset:8192
	s_waitcnt lgkmcnt(1)
	v_mfma_f32_32x32x16_bf16 v[34:49], v[18:21], v[98:101], 0
	ds_read_b128 v[60:63], v167
	ds_read_b128 v[64:67], v167 offset:8192
	v_mov_b64_e32 v[2:3], s[16:17]
	v_mov_b64_e32 v[16:17], s[30:31]
	v_mov_b64_e32 v[4:5], s[18:19]
	v_mov_b64_e32 v[6:7], s[20:21]
	v_mov_b64_e32 v[8:9], s[22:23]
	v_mov_b64_e32 v[10:11], s[24:25]
	s_waitcnt lgkmcnt(2)
	v_mfma_f32_32x32x16_bf16 v[18:33], v[22:25], v[98:101], 0
	v_mov_b64_e32 v[12:13], s[26:27]
	v_mov_b64_e32 v[14:15], s[28:29]
	s_waitcnt lgkmcnt(1)
	v_mfma_f32_32x32x16_bf16 v[34:49], v[60:63], v[102:105], v[34:49]
	v_or_b32_e32 v60, 64, v202
	v_bitop3_b32 v168, v60, v59, v68 bitop3:0xde
	v_add_u32_e32 v169, s4, v168
	s_waitcnt lgkmcnt(0)
	v_mfma_f32_32x32x16_bf16 v[18:33], v[64:67], v[102:105], v[18:33]
	ds_read_b128 v[60:63], v169
	ds_read_b128 v[64:67], v169 offset:8192
	s_waitcnt lgkmcnt(1)
	v_mfma_f32_32x32x16_bf16 v[34:49], v[60:63], v[106:109], v[34:49]
	v_or_b32_e32 v60, 0x60, v202
	v_bitop3_b32 v170, v60, v59, v68 bitop3:0xde
	v_add_u32_e32 v171, s4, v170
	s_waitcnt lgkmcnt(0)
	v_mfma_f32_32x32x16_bf16 v[18:33], v[64:67], v[106:109], v[18:33]
	ds_read_b128 v[60:63], v171
	ds_read_b128 v[64:67], v171 offset:8192
	s_waitcnt lgkmcnt(1)
	v_mfma_f32_32x32x16_bf16 v[34:49], v[60:63], v[110:113], v[34:49]
	v_or_b32_e32 v60, 0x80, v202
	v_bitop3_b32 v172, v60, v59, v68 bitop3:0xde
	v_add_u32_e32 v173, s4, v172
	s_waitcnt lgkmcnt(0)
	v_mfma_f32_32x32x16_bf16 v[18:33], v[64:67], v[110:113], v[18:33]
	ds_read_b128 v[60:63], v173
	ds_read_b128 v[64:67], v173 offset:8192
	s_waitcnt lgkmcnt(1)
	v_mfma_f32_32x32x16_bf16 v[34:49], v[60:63], v[114:117], v[34:49]
	v_or_b32_e32 v60, 0xa0, v202
	v_bitop3_b32 v174, v60, v59, v68 bitop3:0xde
	v_add_u32_e32 v175, s4, v174
	s_waitcnt lgkmcnt(0)
	v_mfma_f32_32x32x16_bf16 v[18:33], v[64:67], v[114:117], v[18:33]
	ds_read_b128 v[60:63], v175
	ds_read_b128 v[64:67], v175 offset:8192
	s_waitcnt lgkmcnt(1)
	v_mfma_f32_32x32x16_bf16 v[34:49], v[60:63], v[118:121], v[34:49]
	v_or_b32_e32 v60, 0xc0, v202
	v_bitop3_b32 v176, v60, v59, v68 bitop3:0xde
	v_add_u32_e32 v177, s4, v176
	s_waitcnt lgkmcnt(0)
	v_mfma_f32_32x32x16_bf16 v[18:33], v[64:67], v[118:121], v[18:33]
	ds_read_b128 v[60:63], v177
	ds_read_b128 v[64:67], v177 offset:8192
	s_waitcnt lgkmcnt(1)
	v_mfma_f32_32x32x16_bf16 v[34:49], v[60:63], v[122:125], v[34:49]
	v_or_b32_e32 v60, 0xe0, v202
	v_bitop3_b32 v178, v60, v59, v68 bitop3:0xde
	v_add_u32_e32 v179, s4, v178
	s_mov_b32 s4, 0x42b504f3
	s_waitcnt lgkmcnt(0)
	v_mfma_f32_32x32x16_bf16 v[18:33], v[64:67], v[122:125], v[18:33]
	ds_read_b128 v[60:63], v179
	ds_read_b128 v[64:67], v179 offset:8192
	s_waitcnt lgkmcnt(1)
	v_mfma_f32_32x32x16_bf16 v[34:49], v[60:63], v[126:129], v[34:49]
	s_waitcnt lgkmcnt(0)
	v_mfma_f32_32x32x16_bf16 v[18:33], v[64:67], v[126:129], v[18:33]
	s_nop 9
	v_max_f32_e32 v59, v35, v35
	v_max_f32_e32 v60, v34, v34
	v_max_f32_e32 v59, v60, v59
	v_max3_f32 v59, v59, v36, v37
	v_max3_f32 v59, v59, v38, v39
	v_max3_f32 v59, v59, v40, v41
	v_max3_f32 v59, v59, v42, v43
	v_max3_f32 v59, v59, v44, v45
	v_max3_f32 v59, v59, v46, v47
	v_max3_f32 v59, v59, v48, v49
	v_max3_f32 v59, v59, v18, v19
	v_max3_f32 v59, v59, v20, v21
	v_max3_f32 v59, v59, v22, v23
	v_max3_f32 v59, v59, v24, v25
	v_max3_f32 v59, v59, v26, v27
	v_max3_f32 v59, v59, v28, v29
	v_max3_f32 v59, v59, v30, v31
	v_max3_f32 v59, v59, v32, v33
	v_mov_b32_e32 v60, v59
	s_nop 1
	v_permlane32_swap_b32_e32 v59, v60
	v_max_f32_e32 v60, v60, v60
	v_max_f32_e32 v59, v59, v59
	v_max_f32_e32 v59, v59, v60
	v_add_f32_e32 v60, 0x7149f2ca, v59
	v_cmp_ge_f32_e32 vcc, s4, v60
	s_cmp_eq_u64 vcc, exec
	s_cselect_b64 vcc, -1, 0
	v_max_f32_e32 v59, 0xf149f2ca, v59
	v_cndmask_b32_e32 v184, v59, v236, vcc
	v_mul_f32_e32 v146, 0xbe0293ee, v184
	v_fmamk_f32 v191, v18, 0x3e0293ee, v146
	v_add_u32_e32 v18, 64, v52
	v_fmamk_f32 v192, v19, 0x3e0293ee, v146
	v_mad_i64_i32 v[18:19], s[4:5], v18, s10, 0
	v_or_b32_e32 v18, v18, v53
	v_fmamk_f32 v195, v22, 0x3e0293ee, v146
	v_fmamk_f32 v187, v26, 0x3e0293ee, v146
	v_fmamk_f32 v188, v27, 0x3e0293ee, v146
	v_lshl_add_u64 v[26:27], v[18:19], 1, s[6:7]
	v_add_u32_e32 v22, 0x60, v52
	v_fmamk_f32 v193, v20, 0x3e0293ee, v146
	v_fmamk_f32 v194, v21, 0x3e0293ee, v146
	v_fmamk_f32 v148, v23, 0x3e0293ee, v146
	global_load_dwordx4 v[18:21], v[26:27], off offset:2560
	v_mad_i64_i32 v[22:23], s[4:5], v22, s10, 0
	v_or_b32_e32 v22, v22, v53
	v_fmamk_f32 v147, v30, 0x3e0293ee, v146
	v_fmamk_f32 v196, v31, 0x3e0293ee, v146
	v_lshl_add_u64 v[30:31], v[22:23], 1, s[6:7]
	v_fmamk_f32 v34, v34, 0x3e0293ee, v146
	v_fmamk_f32 v35, v35, 0x3e0293ee, v146
	v_fmamk_f32 v36, v36, 0x3e0293ee, v146
	v_fmamk_f32 v37, v37, 0x3e0293ee, v146
	v_fmamk_f32 v38, v38, 0x3e0293ee, v146
	v_fmamk_f32 v39, v39, 0x3e0293ee, v146
	v_fmamk_f32 v40, v40, 0x3e0293ee, v146
	v_fmamk_f32 v41, v41, 0x3e0293ee, v146
	v_fmamk_f32 v42, v42, 0x3e0293ee, v146
	v_fmamk_f32 v43, v43, 0x3e0293ee, v146
	v_fmamk_f32 v44, v44, 0x3e0293ee, v146
	v_fmamk_f32 v45, v45, 0x3e0293ee, v146
	v_fmamk_f32 v46, v46, 0x3e0293ee, v146
	v_fmamk_f32 v47, v47, 0x3e0293ee, v146
	v_fmamk_f32 v48, v48, 0x3e0293ee, v146
	v_fmamk_f32 v49, v49, 0x3e0293ee, v146
	v_fmamk_f32 v149, v24, 0x3e0293ee, v146
	v_fmamk_f32 v186, v25, 0x3e0293ee, v146
	v_fmamk_f32 v189, v28, 0x3e0293ee, v146
	v_fmamk_f32 v190, v29, 0x3e0293ee, v146
	v_fmamk_f32 v197, v32, 0x3e0293ee, v146
	v_fmac_f32_e32 v146, 0x3e0293ee, v33
	global_load_dwordx4 v[22:25], v[30:31], off offset:2560
	s_nop 0
	global_load_dwordx4 v[26:29], v[26:27], off offset:2048
	s_nop 0
	global_load_dwordx4 v[30:33], v[30:31], off offset:2048
	v_sub_f32_e32 v60, 0xf149f2ca, v59
	v_mul_f32_e32 v60, 0x3e0293ee, v60
	s_add_i32 s4, 0, 0x10000
	v_exp_f32_e32 v60, v60
	v_add_u32_e32 v181, s4, v54
	s_waitcnt vmcnt(0)
	v_exp_f32_e32 v143, v34
	v_exp_f32_e32 v145, v35
	v_exp_f32_e32 v141, v36
	v_exp_f32_e32 v144, v37
	v_exp_f32_e32 v140, v38
	v_exp_f32_e32 v142, v39
	v_exp_f32_e32 v138, v40
	v_exp_f32_e32 v139, v41
	v_exp_f32_e32 v135, v42
	v_exp_f32_e32 v137, v43
	v_exp_f32_e32 v134, v44
	v_exp_f32_e32 v136, v45
	v_exp_f32_e32 v131, v46
	v_exp_f32_e32 v133, v47
	v_exp_f32_e32 v130, v48
	v_exp_f32_e32 v132, v49
	s_add_i32 s10, 0, 0x18000
	v_add_u32_e32 v182, s4, v56
	v_add_u32_e32 v183, s10, v57
	v_add_u32_e32 v185, s10, v58
	s_addk_i32 s11, 0x4000
	v_cndmask_b32_e64 v180, v60, 1.0, vcc
	v_cmp_gt_u32_e64 s[4:5], 32, v51
	v_add_u32_e32 v158, s11, v55
	v_mov_b64_e32 v[48:49], v[16:17]
	v_mov_b64_e32 v[46:47], v[14:15]
	v_mov_b64_e32 v[44:45], v[12:13]
	v_mov_b64_e32 v[42:43], v[10:11]
	v_mov_b64_e32 v[40:41], v[8:9]
	v_mov_b64_e32 v[38:39], v[6:7]
	v_mov_b64_e32 v[36:37], v[4:5]
	v_mov_b64_e32 v[34:35], v[2:3]
	s_waitcnt vmcnt(3)
	ds_write_b128 v181, v[18:21]
	v_mad_i64_i32 v[18:19], s[6:7], v52, s15, 0
	v_and_b32_e32 v20, 15, v50
	v_mad_i64_i32 v[18:19], s[6:7], s2, v237, v[18:19]
	v_lshlrev_b32_e32 v20, 4, v20
	v_or3_b32 v18, v18, s3, v20
	v_lshl_add_u64 v[152:153], s[52:53], 0, v[18:19]
	v_mov_b64_e32 v[64:65], v[16:17]
	v_mov_b64_e32 v[62:63], v[14:15]
	v_mov_b64_e32 v[60:61], v[12:13]
	v_mov_b64_e32 v[58:59], v[10:11]
	v_mov_b64_e32 v[56:57], v[8:9]
	v_mov_b64_e32 v[54:55], v[6:7]
	v_mov_b64_e32 v[52:53], v[4:5]
	v_mov_b64_e32 v[50:51], v[2:3]
	s_waitcnt vmcnt(2)
	ds_write_b128 v182, v[22:25]
	s_waitcnt vmcnt(1)
	ds_write_b128 v183, v[26:29]
	s_waitcnt vmcnt(0)
	ds_write_b128 v185, v[30:33]
	v_mov_b64_e32 v[32:33], v[16:17]
	v_mov_b64_e32 v[30:31], v[14:15]
	v_mov_b64_e32 v[28:29], v[12:13]
	v_mov_b64_e32 v[26:27], v[10:11]
	v_mov_b64_e32 v[24:25], v[8:9]
	v_mov_b64_e32 v[22:23], v[6:7]
	v_mov_b64_e32 v[20:21], v[4:5]
	v_mov_b64_e32 v[18:19], v[2:3]
	s_waitcnt lgkmcnt(0)
	s_barrier
